# attention tile loops: compiler-inserted vmcnt(0) before V-fragment LDS reads relaxed to vmcnt(8) (tile i+2 DMA stays in flight; tile i+1 was already retired by the explicit counted wait)
# speedup vs baseline: 1.0055x; 1.0055x over previous
; __device__ __forceinline__ float ex2(float v) { return __builtin_amdgcn_exp2f(v); }
; __device__ __forceinline__ int crow(int r, int hi) { return (r & 3) + 8 * (r >> 2) + 4 * hi; }
; #define MFMA32(a, b, c) __builtin_amdgcn_mfma_f32_32x32x16_bf16((a), (b), (c), 0, 0, 0)
; template <bool diag> __device__ __forceinline__ void tileB_post(BStateL& S, const f32x16& y, const bf16x8 (&vf)[4], int ql, int hi) {
;     f32x16 bt, kk;
; #pragma unroll
;     for (int r = 0; r < 16; ++r) {
;         const float t = ex2(__builtin_amdgcn_fmed3f(y[r], -126.f, 126.f));
;         float k_ = __builtin_amdgcn_rcpf(1.0f + t);
;         float b_ = t * k_;
;         if (diag && !(crow(r, hi) < ql)) { b_ = 0.f; k_ = 1.f; }
;         bt[r] = b_; kk[r] = k_;
;     }
;     float G[4], PG[4], tot[4];
; #pragma unroll
;     for (int u = 0; u < 4; ++u) { G[u] = (kk[4 * u] * kk[4 * u + 1]) * (kk[4 * u + 2] * kk[4 * u + 3]); PG[u] = __shfl_xor(G[u], 32); tot[u] = G[u] * PG[u]; }
;     float A[4];
;     A[3] = S.C; A[2] = A[3] * tot[3]; A[1] = A[2] * tot[2]; A[0] = A[1] * tot[1];
;     const float Cn = A[0] * tot[0];
;     f32x16 w;
; #pragma unroll
;     for (int u = 0; u < 4; ++u) {
;         const float F3 = A[u] * (hi == 0 ? PG[u] : 1.0f), F2 = F3 * kk[4 * u + 3], F1 = F2 * kk[4 * u + 2], F0 = F1 * kk[4 * u + 1];
;         w[4 * u + 3] = bt[4 * u + 3] * F3; w[4 * u + 2] = bt[4 * u + 2] * F2; w[4 * u + 1] = bt[4 * u + 1] * F1; w[4 * u] = bt[4 * u] * F0;
;     }
;     S.C = Cn;
;     const bf16x8 p0 = pack8(w, 0), p1 = pack8(w, 8);
;     S.o0 = MFMA32(vf[0], p0, S.o0); S.o0 = MFMA32(vf[1], p1, S.o0);
;     S.o1 = MFMA32(vf[2], p0, S.o1); S.o1 = MFMA32(vf[3], p1, S.o1);
; }
; __device__ __forceinline__ void attnB_wave(LAS unsigned char* st, const bf16* QKV, bf16* O, float* sso, int b, int h, int qi, int lane) {
;     ...
;         if (SB_EARLY_EXIT && __all(!(S.C >= 0x1p-126f))) break;
.LBB0_278:
	s_nop 10
	v_med3_f32 v16, v16, s9, v217
	v_exp_f32_e32 v36, v16
	v_med3_f32 v16, v17, s9, v217
	v_exp_f32_e32 v37, v16
	v_cmp_lt_i32_e32 vcc, v208, v207
	v_add_f32_e32 v16, 1.0, v36
	v_rcp_f32_e32 v38, v16
	v_med3_f32 v16, v18, s9, v217
	v_exp_f32_e32 v40, v16
	v_med3_f32 v18, v19, s9, v217
	v_exp_f32_e32 v42, v18
	v_med3_f32 v18, v20, s9, v217
	v_exp_f32_e32 v43, v18
	v_add_f32_e32 v16, 1.0, v40
	v_rcp_f32_e32 v44, v16
	v_add_f32_e32 v16, 1.0, v42
	v_rcp_f32_e32 v45, v16
	v_add_f32_e32 v16, 1.0, v43
	v_rcp_f32_e32 v46, v16
	v_med3_f32 v16, v21, s9, v217
	v_exp_f32_e32 v47, v16
	v_med3_f32 v19, v22, s9, v217
	v_exp_f32_e32 v84, v19
	v_med3_f32 v19, v23, s9, v217
	v_exp_f32_e32 v85, v19
	v_add_f32_e32 v18, 1.0, v47
	v_rcp_f32_e32 v86, v18
	v_add_f32_e32 v18, 1.0, v84
	v_rcp_f32_e32 v87, v18
	v_add_f32_e32 v18, 1.0, v85
	v_rcp_f32_e32 v88, v18
	v_med3_f32 v18, v24, s9, v217
	v_exp_f32_e32 v89, v18
	v_med3_f32 v21, v25, s9, v217
	v_exp_f32_e32 v25, v21
	v_med3_f32 v21, v26, s9, v217
	v_exp_f32_e32 v90, v21
	v_add_f32_e32 v19, 1.0, v89
	v_rcp_f32_e32 v91, v19
	v_add_f32_e32 v19, 1.0, v25
	v_rcp_f32_e32 v92, v19
	v_add_f32_e32 v19, 1.0, v90
	v_rcp_f32_e32 v93, v19
	v_med3_f32 v19, v27, s9, v217
	v_exp_f32_e32 v27, v19
	v_med3_f32 v23, v30, s9, v217
	v_exp_f32_e32 v30, v23
	v_med3_f32 v23, v31, s9, v217
	v_add_f32_e32 v21, 1.0, v27
	v_rcp_f32_e32 v96, v21
	v_med3_f32 v21, v28, s9, v217
	v_exp_f32_e32 v28, v21
	v_med3_f32 v21, v29, s9, v217
	v_exp_f32_e32 v97, v21
	v_exp_f32_e32 v31, v23
	v_add_f32_e32 v21, 1.0, v28
	v_rcp_f32_e32 v29, v21
	v_add_f32_e32 v21, 1.0, v97
	v_rcp_f32_e32 v111, v21
	v_add_f32_e32 v21, 1.0, v30
	v_add_f32_e32 v17, 1.0, v37
	v_rcp_f32_e32 v113, v21
	v_add_f32_e32 v21, 1.0, v31
	v_rcp_f32_e32 v39, v17
	v_rcp_f32_e32 v138, v21
	v_cndmask_b32_e64 v17, 1.0, v38, s[40:41]
	v_cndmask_b32_e64 v19, 1.0, v91, s[56:57]
	v_cndmask_b32_e64 v41, 1.0, v39, s[42:43]
	v_cndmask_b32_e64 v94, 1.0, v92, s[58:59]
	v_cndmask_b32_e64 v95, 1.0, v93, s[60:61]
	v_cndmask_b32_e64 v110, 1.0, v96, s[62:63]
	v_cndmask_b32_e64 v21, 1.0, v29, s[64:65]
	v_cndmask_b32_e64 v139, 1.0, v111, s[66:67]
	v_cndmask_b32_e64 v140, 1.0, v113, s[68:69]
	v_cndmask_b32_e64 v141, 1.0, v138, s[70:71]
	v_cndmask_b32_e32 v23, v206, v208, vcc
	v_lshlrev_b32_e32 v112, 2, v23
	v_mul_f32_e32 v24, v17, v41
	v_mul_f32_e32 v17, v19, v94
	v_mul_f32_e32 v19, v95, v110
	v_mul_f32_e32 v21, v21, v139
	v_mul_f32_e32 v23, v140, v141
	v_mul_f32_e32 v17, v17, v19
	v_mul_f32_e32 v21, v21, v23
	ds_bpermute_b32 v19, v112, v17
	ds_bpermute_b32 v23, v112, v21
	v_mul_f32_e32 v25, v25, v92
	v_cndmask_b32_e64 v16, 1.0, v46, s[48:49]
	v_mul_f32_e32 v36, v36, v38
	v_mul_f32_e32 v38, v40, v44
	v_mul_f32_e32 v40, v43, v46
	v_cndmask_b32_e64 v46, 0, v25, s[58:59]
	v_mul_f32_e32 v25, v90, v93
	v_cndmask_b32_e64 v18, 1.0, v86, s[50:51]
	v_cndmask_b32_e64 v20, 1.0, v87, s[52:53]
	v_cndmask_b32_e64 v22, 1.0, v88, s[54:55]
	v_mul_f32_e32 v37, v37, v39
	v_mul_f32_e32 v39, v42, v45
	v_mul_f32_e32 v42, v47, v86
	v_cndmask_b32_e64 v47, 0, v25, s[60:61]
	v_mul_f32_e32 v25, v27, v96
	v_mul_f32_e32 v43, v84, v87
	v_cndmask_b32_e64 v84, 0, v25, s[62:63]
	v_mul_f32_e32 v25, v28, v29
	s_waitcnt lgkmcnt(0)
	v_pk_mul_f32 v[16:17], v[16:17], v[18:19]
	v_pk_mul_f32 v[28:29], v[20:21], v[22:23]
	v_cndmask_b32_e64 v82, 1.0, v44, s[44:45]
	v_pk_mul_f32 v[16:17], v[16:17], v[28:29]
	ds_bpermute_b32 v27, v112, v16
	v_cndmask_b32_e64 v83, 1.0, v45, s[46:47]
	v_cndmask_b32_e64 v21, 0, v25, s[64:65]
	v_mul_f32_e32 v25, v97, v111
	v_mul_f32_e32 v26, v82, v83
	v_cndmask_b32_e64 v28, 0, v25, s[66:67]
	v_mov_b32_e32 v25, v16
	s_waitcnt lgkmcnt(0)
	v_pk_mul_f32 v[24:25], v[24:25], v[26:27]
	ds_bpermute_b32 v16, v112, v24
	v_mul_f32_e32 v44, v85, v88
	v_cndmask_b32_e64 v27, 1.0, v27, s[38:39]
	v_cndmask_b32_e64 v44, 0, v44, s[54:55]
	v_cndmask_b32_e64 v36, 0, v36, s[40:41]
	s_waitcnt lgkmcnt(0)
	v_pk_mul_f32 v[86:87], v[24:25], v[16:17]
	v_mul_f32_e32 v17, v27, v17
	v_cndmask_b32_e64 v16, 1.0, v16, s[38:39]
	v_mul_f32_e32 v22, v22, v17
	v_mul_f32_e32 v27, v44, v17
	v_cndmask_b32_e64 v17, 1.0, v19, s[38:39]
	v_mul_f32_e32 v16, v16, v87
	v_mul_f32_e32 v17, v17, v29
	v_mul_f32_e32 v24, v83, v16
	v_mul_f32_e32 v19, v110, v17
	v_mul_f32_e32 v83, v84, v17
	v_cndmask_b32_e64 v17, 1.0, v23, s[38:39]
	v_mul_f32_e32 v25, v82, v24
	v_mul_f32_e32 v20, v20, v22
	v_mul_f32_e32 v23, v141, v17
	v_cndmask_b32_e64 v37, 0, v37, s[42:43]
	v_cndmask_b32_e64 v38, 0, v38, s[44:45]
	v_cndmask_b32_e64 v39, 0, v39, s[46:47]
	v_cndmask_b32_e64 v40, 0, v40, s[48:49]
	v_cndmask_b32_e64 v42, 0, v42, s[50:51]
	v_cndmask_b32_e64 v43, 0, v43, s[52:53]
	v_mul_f32_e32 v45, v89, v91
	v_mul_f32_e32 v26, v30, v113
	v_mul_f32_e32 v30, v31, v138
	v_mul_f32_e32 v31, v41, v25
	v_mul_f32_e32 v18, v18, v20
	v_mul_f32_e32 v29, v95, v19
	v_mul_f32_e32 v82, v140, v23
	v_cndmask_b32_e64 v45, 0, v45, s[56:57]
	v_cndmask_b32_e64 v26, 0, v26, s[68:69]
	v_cndmask_b32_e64 v30, 0, v30, s[70:71]
	v_mul_f32_e32 v39, v39, v16
	v_mul_f32_e32 v24, v38, v24
	v_mul_f32_e32 v16, v37, v25
	v_mul_f32_e32 v25, v36, v31
	v_mul_f32_e32 v22, v43, v22
	v_mul_f32_e32 v20, v42, v20
	v_mul_f32_e32 v18, v40, v18
	v_mul_f32_e32 v31, v94, v29
	v_mul_f32_e32 v85, v139, v82
	v_mul_f32_e32 v84, v47, v19
	v_mul_f32_e32 v29, v46, v29
	v_mul_f32_e32 v31, v45, v31
	v_mul_f32_e32 v30, v30, v17
	v_cvt_pk_bf16_f32 v16, v25, v16
	v_cvt_pk_bf16_f32 v17, v24, v39
	v_cvt_pk_bf16_f32 v18, v18, v20
	v_cvt_pk_bf16_f32 v19, v22, v27
	v_mul_f32_e32 v20, v26, v23
	v_mul_f32_e32 v22, v28, v82
	v_mul_f32_e32 v21, v21, v85
	v_mfma_f32_32x32x16_bf16 v[32:47], v[32:35], v[16:19], 0
	v_cvt_pk_bf16_f32 v82, v31, v29
	v_cvt_pk_bf16_f32 v83, v84, v83
	v_cvt_pk_bf16_f32 v84, v21, v22
	v_cvt_pk_bf16_f32 v85, v20, v30
	v_mul_f32_e32 v111, v86, v87
	v_cmp_nle_f32_e32 vcc, s18, v111
	s_cmp_eq_u64 vcc, exec
	v_mfma_f32_32x32x16_bf16 v[16:31], v[56:59], v[16:19], 0
	s_cselect_b64 s[82:83], -1, 0
	s_or_b64 s[78:79], s[78:79], s[82:83]
	s_and_b64 vcc, exec, s[78:79]
	v_mfma_f32_32x32x16_bf16 v[32:47], v[48:51], v[82:85], v[32:47]
	v_mfma_f32_32x32x16_bf16 v[16:31], v[52:55], v[82:85], v[16:31]
	s_cbranch_vccnz .LBB0_297
; __device__ __forceinline__ void attnB_wave(LAS unsigned char* st, const bf16* QKV, bf16* O, float* sso, int b, int h, int qi, int lane) {
;     ...
;             ATD_VFRAGS(vfc, A, st, (i + 1) & 1);
;             if (i + 3 < n) ATD_DMA(A, st, qi - (i + 3), (i + 1) & 1);
	s_waitcnt vmcnt(8)
	ds_read_b64_tr_b16 v[82:83], v60 offset:12288
	ds_read_b64_tr_b16 v[84:85], v61 offset:12288
	ds_read_b64_tr_b16 v[88:89], v61 offset:14336
	ds_read_b64_tr_b16 v[86:87], v60 offset:14336
	ds_read_b64_tr_b16 v[90:91], v62 offset:12288
	ds_read_b64_tr_b16 v[92:93], v63 offset:12288
	ds_read_b64_tr_b16 v[96:97], v63 offset:14336
	ds_read_b64_tr_b16 v[94:95], v62 offset:14336
	s_waitcnt lgkmcnt(0)
	s_cmp_gt_u32 s81, 2
	s_mov_b64 s[78:79], -1
	s_cbranch_scc0 .LBB0_281
	s_mul_i32 s3, s81, 0x18000
	s_add_i32 s10, s3, 0xfffb8000
	s_lshl_b64 s[78:79], s[10:11], 1
	v_lshl_add_u64 v[48:49], v[102:103], 0, s[78:79]
	v_lshl_add_u64 v[50:51], v[48:49], 0, s[22:23]
	s_add_i32 m0, s33, 0x2000
	v_readlane_b32 s10, v255, 32
	global_load_lds_dwordx4 v[50:51], off
	v_lshl_add_u64 v[50:51], v[104:105], 0, s[78:79]
	v_lshl_add_u64 v[52:53], v[50:51], 0, s[74:75]
	s_mov_b32 m0, s10
	v_readlane_b32 s10, v255, 33
	global_load_lds_dwordx4 v[52:53], off
	v_lshl_add_u64 v[48:49], v[48:49], 0, s[76:77]
	s_mov_b32 m0, s10
	v_readlane_b32 s10, v255, 34
	global_load_lds_dwordx4 v[48:49], off
	v_lshl_add_u64 v[48:49], v[50:51], 0, s[24:25]
	s_mov_b32 m0, s10
	v_readlane_b32 s10, v255, 35
	global_load_lds_dwordx4 v[48:49], off
	v_lshl_add_u64 v[48:49], v[106:107], 0, s[78:79]
	s_mov_b32 m0, s10
	v_lshl_add_u64 v[50:51], v[108:109], 0, s[78:79]
	v_readlane_b32 s10, v255, 36
	global_load_lds_dwordx4 v[48:49], off
	v_lshl_add_u64 v[52:53], v[50:51], 0, s[26:27]
	s_mov_b32 m0, s10
	v_readlane_b32 s10, v255, 37
	global_load_lds_dwordx4 v[52:53], off
	v_lshl_add_u64 v[48:49], v[48:49], 0, s[28:29]
	s_mov_b32 m0, s10
	s_mov_b64 s[78:79], 0
	global_load_lds_dwordx4 v[48:49], off
	v_lshl_add_u64 v[48:49], v[50:51], 0, s[30:31]
	s_mov_b32 m0, s8
	s_nop 0
	global_load_lds_dwordx4 v[48:49], off

; __device__ __forceinline__ float ex2(float v) { return __builtin_amdgcn_exp2f(v); }
; __device__ __forceinline__ int crow(int r, int hi) { return (r & 3) + 8 * (r >> 2) + 4 * hi; }
; #define MFMA32(a, b, c) __builtin_amdgcn_mfma_f32_32x32x16_bf16((a), (b), (c), 0, 0, 0)
; template <bool diag> __device__ __forceinline__ void tileB_post(BStateL& S, const f32x16& y, const bf16x8 (&vf)[4], int ql, int hi) {
;     f32x16 bt, kk;
; #pragma unroll
;     for (int r = 0; r < 16; ++r) {
;         const float t = ex2(__builtin_amdgcn_fmed3f(y[r], -126.f, 126.f));
;         float k_ = __builtin_amdgcn_rcpf(1.0f + t);
;         float b_ = t * k_;
;         if (diag && !(crow(r, hi) < ql)) { b_ = 0.f; k_ = 1.f; }
;         bt[r] = b_; kk[r] = k_;
;     }
;     float G[4], PG[4], tot[4];
; #pragma unroll
;     for (int u = 0; u < 4; ++u) { G[u] = (kk[4 * u] * kk[4 * u + 1]) * (kk[4 * u + 2] * kk[4 * u + 3]); PG[u] = __shfl_xor(G[u], 32); tot[u] = G[u] * PG[u]; }
;     float A[4];
;     A[3] = S.C; A[2] = A[3] * tot[3]; A[1] = A[2] * tot[2]; A[0] = A[1] * tot[1];
;     const float Cn = A[0] * tot[0];
;     f32x16 w;
; #pragma unroll
;     for (int u = 0; u < 4; ++u) {
;         const float F3 = A[u] * (hi == 0 ? PG[u] : 1.0f), F2 = F3 * kk[4 * u + 3], F1 = F2 * kk[4 * u + 2], F0 = F1 * kk[4 * u + 1];
;         w[4 * u + 3] = bt[4 * u + 3] * F3; w[4 * u + 2] = bt[4 * u + 2] * F2; w[4 * u + 1] = bt[4 * u + 1] * F1; w[4 * u] = bt[4 * u] * F0;
;     }
;     S.C = Cn;
;     const bf16x8 p0 = pack8(w, 0), p1 = pack8(w, 8);
;     S.o0 = MFMA32(vf[0], p0, S.o0); S.o0 = MFMA32(vf[1], p1, S.o0);
;     S.o1 = MFMA32(vf[2], p0, S.o1); S.o1 = MFMA32(vf[3], p1, S.o1);
; }
; __device__ __forceinline__ void attnB_wave(LAS unsigned char* st, const bf16* QKV, bf16* O, float* sso, int b, int h, int qi, int lane) {
;     ...
;         if (SB_EARLY_EXIT && __all(!(S.C >= 0x1p-126f))) break;
.LBB0_293:
	v_med3_f32 v110, v48, s9, v217
	v_exp_f32_e32 v138, v110
	v_med3_f32 v110, v49, s9, v217
	v_exp_f32_e32 v139, v110
	s_mov_b64 s[84:85], -1
	v_add_f32_e32 v110, 1.0, v138
	v_rcp_f32_e32 v140, v110
	v_med3_f32 v110, v50, s9, v217
	v_add_f32_e32 v113, 1.0, v139
	v_exp_f32_e32 v142, v110
	v_med3_f32 v110, v51, s9, v217
	v_exp_f32_e32 v143, v110
	v_rcp_f32_e32 v141, v113
	v_med3_f32 v113, v52, s9, v217
	v_exp_f32_e32 v146, v113
	v_med3_f32 v113, v53, s9, v217
	v_exp_f32_e32 v147, v113
	v_med3_f32 v113, v54, s9, v217
	v_add_f32_e32 v110, 1.0, v142
	v_exp_f32_e32 v156, v113
	v_med3_f32 v113, v55, s9, v217
	v_rcp_f32_e32 v144, v110
	v_add_f32_e32 v110, 1.0, v143
	v_exp_f32_e32 v157, v113
	v_med3_f32 v113, v56, s9, v217
	v_rcp_f32_e32 v145, v110
	v_add_f32_e32 v110, 1.0, v146
	v_exp_f32_e32 v160, v113
	v_med3_f32 v113, v57, s9, v217
	v_rcp_f32_e32 v148, v110
	v_add_f32_e32 v110, 1.0, v147
	v_exp_f32_e32 v161, v113
	v_med3_f32 v113, v58, s9, v217
	v_rcp_f32_e32 v149, v110
	v_add_f32_e32 v110, 1.0, v156
	v_exp_f32_e32 v176, v113
	v_med3_f32 v113, v59, s9, v217
	v_rcp_f32_e32 v158, v110
	v_add_f32_e32 v110, 1.0, v157
	v_exp_f32_e32 v177, v113
	v_med3_f32 v113, v60, s9, v217
	v_rcp_f32_e32 v159, v110
	v_add_f32_e32 v110, 1.0, v160
	v_exp_f32_e32 v180, v113
	v_med3_f32 v113, v61, s9, v217
	v_rcp_f32_e32 v174, v110
	v_add_f32_e32 v110, 1.0, v161
	v_exp_f32_e32 v181, v113
	v_med3_f32 v113, v63, s9, v217
	v_rcp_f32_e32 v175, v110
	v_add_f32_e32 v110, 1.0, v176
	v_exp_f32_e32 v185, v113
	v_med3_f32 v113, v62, s9, v217
	v_rcp_f32_e32 v178, v110
	v_add_f32_e32 v110, 1.0, v177
	v_exp_f32_e32 v184, v113
	v_rcp_f32_e32 v179, v110
	v_add_f32_e32 v110, 1.0, v180
	v_rcp_f32_e32 v182, v110
	v_add_f32_e32 v110, 1.0, v181
	v_rcp_f32_e32 v183, v110
	v_add_f32_e32 v110, 1.0, v185
	v_rcp_f32_e32 v187, v110
	v_add_f32_e32 v110, 1.0, v184
	v_rcp_f32_e32 v186, v110
	v_mov_b32_e32 v188, v183
	v_mov_b32_e32 v189, v187
	v_mov_b32_e32 v190, v182
	v_mov_b32_e32 v191, v186
	v_pk_mul_f32 v[188:189], v[190:191], v[188:189]
	v_mov_b32_e32 v190, v175
	v_pk_mul_f32 v[188:189], v[188:189], v[188:189] op_sel:[0,1] op_sel_hi:[1,0]
	ds_bpermute_b32 v189, v112, v188
	v_mov_b32_e32 v191, v179
	v_mov_b32_e32 v192, v174
	v_mov_b32_e32 v193, v178
	v_pk_mul_f32 v[190:191], v[192:193], v[190:191]
	v_mov_b32_e32 v193, v188
	v_mov_b32_e32 v192, v190
	v_mov_b32_e32 v188, v191
	s_waitcnt lgkmcnt(0)
	v_pk_mul_f32 v[190:191], v[192:193], v[188:189]
	ds_bpermute_b32 v110, v112, v190
	v_mov_b32_e32 v192, v149
	v_mov_b32_e32 v193, v159
	v_mov_b32_e32 v194, v148
	v_mov_b32_e32 v195, v158
	s_waitcnt lgkmcnt(0)
	v_pk_mul_f32 v[190:191], v[190:191], v[110:111]
	v_pk_mul_f32 v[192:193], v[194:195], v[192:193]
	v_mov_b32_e32 v195, v190
	v_mov_b32_e32 v194, v192
	v_mov_b32_e32 v190, v193
	v_pk_mul_f32 v[192:193], v[194:195], v[190:191]
	ds_bpermute_b32 v195, v112, v192
	v_mov_b32_e32 v196, v141
	v_mov_b32_e32 v197, v145
	v_mov_b32_e32 v198, v140
	v_mov_b32_e32 v199, v144
	v_pk_mul_f32 v[196:197], v[198:199], v[196:197]
	v_mov_b32_e32 v199, v192
	v_mov_b32_e32 v198, v196
	v_mov_b32_e32 v194, v197
	s_waitcnt lgkmcnt(0)
	v_pk_mul_f32 v[196:197], v[198:199], v[194:195]
	ds_bpermute_b32 v192, v112, v196
	v_cndmask_b32_e64 v113, 1.0, v195, s[38:39]
	v_pk_mul_f32 v[138:139], v[138:139], v[140:141]
	v_pk_mul_f32 v[142:143], v[142:143], v[144:145]
	v_pk_mul_f32 v[156:157], v[156:157], v[158:159]
	s_waitcnt lgkmcnt(0)
	v_pk_mul_f32 v[194:195], v[196:197], v[192:193]
	v_cndmask_b32_e64 v140, 1.0, v192, s[38:39]
	v_mul_f32_e32 v197, v140, v195
	v_mul_f32_e32 v196, v145, v197
	v_mul_f32_e32 v145, v144, v196
	v_mul_f32_e32 v144, v141, v145
	v_pk_mul_f32 v[140:141], v[142:143], v[196:197]
	v_mul_f32_e32 v143, v113, v193
	v_mul_f32_e32 v142, v159, v143
	v_pk_mul_f32 v[138:139], v[138:139], v[144:145]
	v_mul_f32_e32 v145, v158, v142
	v_pk_mul_f32 v[146:147], v[146:147], v[148:149]
	v_mul_f32_e32 v144, v149, v145
	v_pk_mul_f32 v[142:143], v[156:157], v[142:143]
	v_pk_mul_f32 v[144:145], v[146:147], v[144:145]
	v_cvt_pk_bf16_f32 v138, v138, v139
	v_cvt_pk_bf16_f32 v139, v140, v141
	v_cvt_pk_bf16_f32 v140, v144, v145
	v_cvt_pk_bf16_f32 v141, v142, v143
	v_cndmask_b32_e64 v110, 1.0, v110, s[38:39]
	v_mul_f32_e32 v147, v110, v191
	v_mfma_f32_32x32x16_bf16 v[32:47], v[82:85], v[138:141], v[32:47]
	v_cndmask_b32_e64 v110, 1.0, v189, s[38:39]
	v_mul_f32_e32 v111, v111, v110
	v_mul_f32_e32 v146, v179, v147
	v_mul_f32_e32 v110, v187, v111
	v_mul_f32_e32 v149, v178, v146
	v_mul_f32_e32 v157, v186, v110
	v_pk_mul_f32 v[184:185], v[184:185], v[186:187]
	v_mfma_f32_32x32x16_bf16 v[16:31], v[90:93], v[138:141], v[16:31]
	v_mul_f32_e64 v180, v180, v182
	v_mul_f32_e64 v181, v181, v183
	v_mul_f32_e64 v176, v176, v178
	v_mul_f32_e64 v177, v177, v179
	v_mul_f32_e64 v160, v160, v174
	v_mul_f32_e64 v161, v161, v175
	v_mul_f32_e32 v148, v175, v149
	v_mul_f32_e32 v156, v183, v157
	v_pk_mul_f32 v[146:147], v[176:177], v[146:147]
	v_pk_mul_f32 v[148:149], v[160:161], v[148:149]
	v_pk_mul_f32 v[110:111], v[184:185], v[110:111]
	v_pk_mul_f32 v[144:145], v[180:181], v[156:157]
	v_cvt_pk_bf16_f32 v142, v148, v149
	v_cvt_pk_bf16_f32 v143, v146, v147
	v_cvt_pk_bf16_f32 v144, v144, v145
	v_cvt_pk_bf16_f32 v145, v110, v111
	v_mul_f32_e32 v111, v194, v195
	v_cmp_nle_f32_e32 vcc, s18, v111
	v_mfma_f32_32x32x16_bf16 v[32:47], v[86:89], v[142:145], v[32:47]
	s_cmp_eq_u64 vcc, exec
	v_mfma_f32_32x32x16_bf16 v[16:31], v[94:97], v[142:145], v[16:31]
	s_cbranch_scc1 .LBB0_286
; __device__ __forceinline__ void attnB_wave(LAS unsigned char* st, const bf16* QKV, bf16* O, float* sso, int b, int h, int qi, int lane) {
;     ...
;             ATD_VFRAGS(vfc, A, st, (i + 1) & 1);
;             if (i + 3 < n) ATD_DMA(A, st, qi - (i + 3), (i + 1) & 1);
	s_andn2_b64 vcc, exec, s[78:79]
	s_cbranch_vccnz .LBB0_285
	s_and_b32 s78, s3, 0x2000
	s_add_i32 s78, s33, s78
	v_add_u32_e32 v48, s78, v152
	v_add_u32_e32 v49, s78, v153
	s_waitcnt vmcnt(8)
	ds_read_b64_tr_b16 v[82:83], v48 offset:4096
	ds_read_b64_tr_b16 v[84:85], v49 offset:4096
	ds_read_b64_tr_b16 v[88:89], v49 offset:6144
	ds_read_b64_tr_b16 v[86:87], v48 offset:6144
	v_add_u32_e32 v48, s78, v154
	v_add_u32_e32 v49, s78, v155
	ds_read_b64_tr_b16 v[90:91], v48 offset:4096
	ds_read_b64_tr_b16 v[92:93], v49 offset:4096
	ds_read_b64_tr_b16 v[96:97], v49 offset:6144
	ds_read_b64_tr_b16 v[94:95], v48 offset:6144
	s_waitcnt lgkmcnt(0)
	s_add_i32 s79, s82, 4
	s_cmp_gt_u32 s79, s81
	s_cbranch_scc1 .LBB0_284
	s_lshl_b64 s[82:83], s[10:11], 1
	v_lshl_add_u64 v[48:49], v[102:103], 0, s[82:83]
	s_mov_b32 m0, s78
	v_lshl_add_u64 v[50:51], v[48:49], 0, s[22:23]
	global_load_lds_dwordx4 v[50:51], off
	v_lshl_add_u64 v[50:51], v[104:105], 0, s[82:83]
	v_lshl_add_u64 v[52:53], v[50:51], 0, s[74:75]
	s_add_i32 m0, s78, 0x400
	v_lshl_add_u64 v[48:49], v[48:49], 0, s[76:77]
	global_load_lds_dwordx4 v[52:53], off
	s_add_i32 m0, s78, 0x800
	s_nop 0
	global_load_lds_dwordx4 v[48:49], off
	v_lshl_add_u64 v[48:49], v[50:51], 0, s[24:25]
	s_add_i32 m0, s78, 0xc00
	v_lshl_add_u64 v[50:51], v[108:109], 0, s[82:83]
	global_load_lds_dwordx4 v[48:49], off
	v_lshl_add_u64 v[48:49], v[106:107], 0, s[82:83]
	s_add_i32 m0, s78, 0x1000
	v_lshl_add_u64 v[52:53], v[50:51], 0, s[26:27]
	global_load_lds_dwordx4 v[48:49], off
	s_add_i32 m0, s78, 0x1400
	v_lshl_add_u64 v[48:49], v[48:49], 0, s[28:29]
	global_load_lds_dwordx4 v[52:53], off
	s_add_i32 m0, s78, 0x1800
	s_nop 0
	global_load_lds_dwordx4 v[48:49], off
	v_lshl_add_u64 v[48:49], v[50:51], 0, s[30:31]
	s_add_i32 m0, s78, 0x1c00
	s_nop 0
	global_load_lds_dwordx4 v[48:49], off
	s_branch .LBB0_284

; __device__ __forceinline__ float ex2(float v) { return __builtin_amdgcn_exp2f(v); }
; #define MFMA32(a, b, c) __builtin_amdgcn_mfma_f32_32x32x16_bf16((a), (b), (c), 0, 0, 0)
; __device__ __forceinline__ void tileA_post(AState& S, f32x16& s, const bf16x8 (&vf)[4], const LAS float* tb2, int kbase, int q0, int ql, int hi) {
;     ...
;     float mx = s[0];
; #pragma unroll
;     for (int r = 1; r < 16; ++r) mx = fmaxf(mx, s[r]);
;     mx = fmaxf(mx, __shfl_xor(mx, 32));
;     const float mnew = fmaxf(S.mrun, mx), alpha = ex2(S.mrun - mnew);
;     S.mrun = mnew;
;     float rs = 0.f;
; #pragma unroll
;     for (int r = 0; r < 16; ++r) { s[r] = ex2(s[r] - mnew); rs += s[r]; }
;     S.l = S.l * alpha + rs;
; #pragma unroll
;     for (int r = 0; r < 16; ++r) { S.o0[r] *= alpha; S.o1[r] *= alpha; }
;     const bf16x8 p0 = pack8(s, 0), p1 = pack8(s, 8);
;     S.o0 = MFMA32(vf[0], p0, S.o0); S.o0 = MFMA32(vf[1], p1, S.o0);
;     S.o1 = MFMA32(vf[2], p0, S.o1); S.o1 = MFMA32(vf[3], p1, S.o1);
; __device__ __forceinline__ void attnA_wave(LAS unsigned char* st, const LAS float* tb2, const bf16* QKV, bf16* O, float* sso, int b, int h, int qblk, int lane) {
;     ...
;             ATD_VFRAGS(vfc, A, st, (i + 1) & 1);
;             if (i + 3 < n) ATD_DMA(A, st, t0 + i + 3, (i + 1) & 1);
.LBB0_313:
	s_nop 0
	v_max_f32_e32 v65, v49, v49
	v_max_f32_e32 v66, v48, v48
	v_max_f32_e32 v65, v66, v65
	v_max3_f32 v65, v65, v50, v51
	v_max3_f32 v65, v65, v52, v53
	v_max3_f32 v65, v65, v54, v55
	v_max3_f32 v65, v65, v56, v57
	v_max3_f32 v65, v65, v58, v59
	v_cmp_lt_i32_e32 vcc, v208, v207
	v_max3_f32 v65, v65, v60, v61
	v_max3_f32 v65, v65, v62, v63
	v_cndmask_b32_e32 v66, v206, v208, vcc
	v_lshlrev_b32_e32 v66, 2, v66
	ds_bpermute_b32 v66, v66, v65
	s_andn2_b64 vcc, exec, s[78:79]
	s_waitcnt lgkmcnt(0)
	v_max3_f32 v186, v64, v65, v66
	v_sub_f32_e32 v48, v48, v186
	v_sub_f32_e32 v80, v64, v186
	v_exp_f32_e32 v64, v48
	v_sub_f32_e32 v48, v49, v186
	v_exp_f32_e32 v65, v48
	v_sub_f32_e32 v48, v50, v186
	v_exp_f32_e32 v66, v48
	v_sub_f32_e32 v48, v51, v186
	v_exp_f32_e32 v67, v48
	v_sub_f32_e32 v48, v52, v186
	v_exp_f32_e32 v68, v48
	v_sub_f32_e32 v48, v53, v186
	v_exp_f32_e32 v69, v48
	v_sub_f32_e32 v48, v54, v186
	v_exp_f32_e32 v70, v48
	v_sub_f32_e32 v48, v55, v186
	v_exp_f32_e32 v71, v48
	v_sub_f32_e32 v48, v56, v186
	v_exp_f32_e32 v72, v48
	v_sub_f32_e32 v48, v57, v186
	v_exp_f32_e32 v73, v48
	v_sub_f32_e32 v48, v58, v186
	v_exp_f32_e32 v74, v48
	v_sub_f32_e32 v48, v59, v186
	v_exp_f32_e32 v75, v48
	v_sub_f32_e32 v48, v60, v186
	v_exp_f32_e32 v80, v80
	v_exp_f32_e32 v76, v48
	v_sub_f32_e32 v48, v61, v186
	v_exp_f32_e32 v77, v48
	v_sub_f32_e32 v48, v62, v186
	v_exp_f32_e32 v78, v48
	v_sub_f32_e32 v48, v63, v186
	v_exp_f32_e32 v79, v48
	v_pk_mul_f32 v[14:15], v[14:15], v[80:81] op_sel_hi:[1,0]
	v_pk_mul_f32 v[12:13], v[12:13], v[80:81] op_sel_hi:[1,0]
	v_pk_mul_f32 v[10:11], v[10:11], v[80:81] op_sel_hi:[1,0]
	v_pk_mul_f32 v[8:9], v[8:9], v[80:81] op_sel_hi:[1,0]
	v_pk_mul_f32 v[6:7], v[6:7], v[80:81] op_sel_hi:[1,0]
	v_pk_mul_f32 v[4:5], v[4:5], v[80:81] op_sel_hi:[1,0]
	v_pk_mul_f32 v[2:3], v[2:3], v[80:81] op_sel_hi:[1,0]
	v_pk_mul_f32 v[0:1], v[0:1], v[80:81] op_sel_hi:[1,0]
	v_pk_mul_f32 v[30:31], v[30:31], v[80:81] op_sel_hi:[1,0]
	v_pk_mul_f32 v[28:29], v[28:29], v[80:81] op_sel_hi:[1,0]
	v_pk_mul_f32 v[26:27], v[26:27], v[80:81] op_sel_hi:[1,0]
	v_pk_mul_f32 v[24:25], v[24:25], v[80:81] op_sel_hi:[1,0]
	v_pk_mul_f32 v[22:23], v[22:23], v[80:81] op_sel_hi:[1,0]
	v_pk_mul_f32 v[20:21], v[20:21], v[80:81] op_sel_hi:[1,0]
	v_pk_mul_f32 v[18:19], v[18:19], v[80:81] op_sel_hi:[1,0]
	v_pk_mul_f32 v[16:17], v[16:17], v[80:81] op_sel_hi:[1,0]
	v_cvt_pk_bf16_f32 v48, v64, v65
	v_cvt_pk_bf16_f32 v49, v66, v67
	v_cvt_pk_bf16_f32 v50, v68, v69
	v_cvt_pk_bf16_f32 v51, v70, v71
	v_cvt_pk_bf16_f32 v52, v72, v73
	v_cvt_pk_bf16_f32 v53, v74, v75
	v_mfma_f32_32x32x16_bf16 v[0:15], v[98:101], v[48:51], v[0:15]
	v_cvt_pk_bf16_f32 v54, v76, v77
	v_cvt_pk_bf16_f32 v55, v78, v79
	v_mfma_f32_32x32x16_bf16 v[16:31], v[106:109], v[48:51], v[16:31]
	s_nop 0
	v_mfma_f32_32x32x16_bf16 v[0:15], v[102:105], v[52:55], v[0:15]
	v_mfma_f32_32x32x16_bf16 v[16:31], v[110:113], v[52:55], v[16:31]
	s_cbranch_vccnz .LBB0_323
	s_and_b32 s78, s90, 0x2000
	s_add_i32 s78, s33, s78
	v_add_u32_e32 v48, s78, v152
	v_add_u32_e32 v49, s78, v153
	s_waitcnt vmcnt(8)
	ds_read_b64_tr_b16 v[98:99], v48 offset:4096
	ds_read_b64_tr_b16 v[100:101], v49 offset:4096
	ds_read_b64_tr_b16 v[104:105], v49 offset:6144
	ds_read_b64_tr_b16 v[102:103], v48 offset:6144
	v_add_u32_e32 v48, s78, v154
	v_add_u32_e32 v49, s78, v155
	ds_read_b64_tr_b16 v[106:107], v48 offset:4096
	ds_read_b64_tr_b16 v[108:109], v49 offset:4096
	ds_read_b64_tr_b16 v[112:113], v49 offset:6144
	ds_read_b64_tr_b16 v[110:111], v48 offset:6144
	s_waitcnt lgkmcnt(0)
	s_cmp_ge_i32 s3, s88
	s_cbranch_scc1 .LBB0_316
	s_addk_i32 s94, 0x60
	v_mad_i64_i32 v[48:49], s[84:85], s94, v218, v[142:143]
	s_mov_b32 m0, s78
	v_lshl_add_u64 v[50:51], v[48:49], 0, s[34:35]
	global_load_lds_dwordx4 v[50:51], off
	v_mad_i64_i32 v[50:51], s[84:85], s94, v218, v[144:145]
	v_lshl_add_u64 v[52:53], v[50:51], 0, s[96:97]
	s_add_i32 m0, s78, 0x400
	v_lshl_add_u64 v[48:49], v[48:49], 0, s[72:73]
	global_load_lds_dwordx4 v[52:53], off
	s_add_i32 m0, s78, 0x800
	s_nop 0
	global_load_lds_dwordx4 v[48:49], off
	v_lshl_add_u64 v[48:49], v[50:51], 0, s[6:7]
	s_add_i32 m0, s78, 0xc00
	v_mad_i64_i32 v[50:51], s[84:85], s94, v218, v[148:149]
	global_load_lds_dwordx4 v[48:49], off
	v_mad_i64_i32 v[48:49], s[84:85], s94, v218, v[146:147]
	s_add_i32 m0, s78, 0x1000
	v_lshl_add_u64 v[52:53], v[50:51], 0, s[26:27]
	global_load_lds_dwordx4 v[48:49], off
	s_add_i32 m0, s78, 0x1400
	v_lshl_add_u64 v[48:49], v[48:49], 0, s[28:29]
	global_load_lds_dwordx4 v[52:53], off
	s_add_i32 m0, s78, 0x1800
	s_nop 0
	global_load_lds_dwordx4 v[48:49], off
	v_lshl_add_u64 v[48:49], v[50:51], 0, s[30:31]
	s_add_i32 m0, s78, 0x1c00
	s_nop 0
	global_load_lds_dwordx4 v[48:49], off
